# v36 + x-rmsnorm row loop software-pipelined: next row's 8 x loads prefetched into a second register set while the current row is reduced/stored
# baseline (speedup 1.0000x reference)
.LBB0_83:
	s_cmpk_gt_i32 s26, 0x3fff
	s_cbranch_scc1 .LBB0_86
	v_mbcnt_lo_u32_b32 v2, -1, 0
	v_mbcnt_hi_u32_b32 v2, -1, v2
	v_and_b32_e32 v3, 64, v2
	v_add_u32_e32 v3, 64, v3
	v_xor_b32_e32 v4, 1, v2
	v_cmp_lt_i32_e32 vcc, v4, v3
	s_ashr_i32 s27, s26, 31
	s_lshl_b64 s[6:7], s[26:27], 12
	v_cndmask_b32_e32 v4, v2, v4, vcc
	v_lshlrev_b32_e32 v33, 2, v4
	v_xor_b32_e32 v4, 2, v2
	v_cmp_lt_i32_e32 vcc, v4, v3
	s_add_u32 s6, s8, s6
	s_addc_u32 s7, s9, s7
	v_cndmask_b32_e32 v4, v2, v4, vcc
	v_lshlrev_b32_e32 v34, 2, v4
	v_xor_b32_e32 v4, 4, v2
	v_cmp_lt_i32_e32 vcc, v4, v3
	s_ashr_i32 s35, s34, 31
	s_mov_b64 s[0:1], 0x1000
	v_cndmask_b32_e32 v4, v2, v4, vcc
	v_lshlrev_b32_e32 v35, 2, v4
	v_xor_b32_e32 v4, 8, v2
	v_cmp_lt_i32_e32 vcc, v4, v3
	s_lshl_b64 s[10:11], s[26:27], 13
	v_mov_b32_e32 v39, 0x358637bd
	v_cndmask_b32_e32 v4, v2, v4, vcc
	v_lshlrev_b32_e32 v36, 2, v4
	v_xor_b32_e32 v4, 16, v2
	v_cmp_lt_i32_e32 vcc, v4, v3
	s_mov_b32 s12, 0xf800000
	v_mov_b32_e32 v40, 0x260
	v_cndmask_b32_e32 v4, v2, v4, vcc
	v_lshlrev_b32_e32 v37, 2, v4
	v_xor_b32_e32 v4, 32, v2
	v_cmp_lt_i32_e32 vcc, v4, v3
	v_mov_b32_e32 v3, 0
	v_mov_b32_e32 v5, v3
	v_cndmask_b32_e32 v2, v2, v4, vcc
	v_lshlrev_b32_e32 v4, 3, v208
	v_lshlrev_b32_e32 v38, 2, v2
	v_lshlrev_b32_e32 v2, 4, v208
	v_lshl_add_u64 v[4:5], s[6:7], 0, v[4:5]
	s_mov_b64 s[6:7], 0x8000000
	v_lshl_add_u64 v[18:19], s[58:59], 0, v[2:3]
	v_lshl_add_u64 v[28:29], v[4:5], 0, s[6:7]
	s_lshl_b64 s[6:7], s[34:35], 12
	v_lshl_add_u64 v[20:21], v[18:19], 0, s[0:1]
	s_mov_b64 s[0:1], 0x1400
	s_add_u32 s10, s52, s10
	v_lshl_add_u64 v[22:23], v[18:19], 0, s[0:1]
	s_mov_b64 s[0:1], 0x1800
	s_addc_u32 s11, s53, s11
	v_lshl_add_u64 v[24:25], v[18:19], 0, s[0:1]
	s_mov_b64 s[0:1], 0x1c00
	v_lshl_add_u64 v[2:3], s[10:11], 0, v[2:3]
	v_lshl_add_u64 v[26:27], v[18:19], 0, s[0:1]
	v_lshl_add_u64 v[30:31], v[2:3], 0, s[0:1]
	s_lshl_b64 s[10:11], s[34:35], 13
	s_movk_i32 s13, 0x7fff
	v_mov_b32_e32 v41, 1
	s_mov_b32 s14, s26
	global_load_dwordx4 v[140:143], v[18:19], off
	global_load_dwordx4 v[144:147], v[18:19], off offset:1024
	global_load_dwordx4 v[148:151], v[18:19], off offset:2048
	global_load_dwordx4 v[152:155], v[18:19], off offset:3072
	global_load_dwordx4 v[156:159], v[20:21], off
	global_load_dwordx4 v[160:163], v[22:23], off
	global_load_dwordx4 v[164:167], v[24:25], off
	global_load_dwordx4 v[168:171], v[26:27], off
	s_waitcnt vmcnt(0)
	v_add_co_u32_e32 v62, vcc, 0xfffff000, v30
	s_nop 1
	v_addc_co_u32_e32 v63, vcc, -1, v31, vcc
	global_load_dwordx4 v[172:175], v[30:31], off offset:-3072
	global_load_dwordx4 v[176:179], v[30:31], off offset:-2048
	global_load_dwordx4 v[180:183], v[30:31], off
	global_load_dwordx4 v[184:187], v[30:31], off offset:-1024
	global_load_dwordx4 v[188:191], v[62:63], off offset:-3072
	global_load_dwordx4 v[192:195], v[62:63], off offset:-2048
	global_load_dwordx4 v[196:199], v[62:63], off offset:-1024
	global_load_dwordx4 v[200:203], v[30:31], off offset:-4096
.LBB0_85:
	s_add_i32 s14, s14, s34
	s_cmpk_gt_i32 s14, 0x3fff
	v_lshl_add_u64 v[30:31], v[30:31], 0, s[10:11]
	s_waitcnt vmcnt(0)
	v_mov_b64_e32 v[14:15], v[172:173]
	v_mov_b64_e32 v[16:17], v[174:175]
	v_mov_b64_e32 v[10:11], v[176:177]
	v_mov_b64_e32 v[12:13], v[178:179]
	v_mov_b64_e32 v[2:3], v[180:181]
	v_mov_b64_e32 v[4:5], v[182:183]
	v_mov_b64_e32 v[6:7], v[184:185]
	v_mov_b64_e32 v[8:9], v[186:187]
	v_mov_b64_e32 v[46:47], v[188:189]
	v_mov_b64_e32 v[48:49], v[190:191]
	v_mov_b64_e32 v[50:51], v[192:193]
	v_mov_b64_e32 v[52:53], v[194:195]
	v_mov_b64_e32 v[54:55], v[196:197]
	v_mov_b64_e32 v[56:57], v[198:199]
	v_mov_b64_e32 v[58:59], v[200:201]
	v_mov_b64_e32 v[60:61], v[202:203]
	v_mov_b64_e32 v[42:43], v[140:141]
	v_mov_b64_e32 v[44:45], v[142:143]
	s_cbranch_scc1 .Lmy_rms_nopf
	v_add_co_u32_e32 v62, vcc, 0xfffff000, v30
	s_nop 1
	v_addc_co_u32_e32 v63, vcc, -1, v31, vcc
	global_load_dwordx4 v[172:175], v[30:31], off offset:-3072
	global_load_dwordx4 v[176:179], v[30:31], off offset:-2048
	global_load_dwordx4 v[180:183], v[30:31], off
	global_load_dwordx4 v[184:187], v[30:31], off offset:-1024
	global_load_dwordx4 v[188:191], v[62:63], off offset:-3072
	global_load_dwordx4 v[192:195], v[62:63], off offset:-2048
	global_load_dwordx4 v[196:199], v[62:63], off offset:-1024
	global_load_dwordx4 v[200:203], v[30:31], off offset:-4096
.Lmy_rms_nopf:
	v_mul_f32_e32 v84, v14, v14
	v_pk_mul_f32 v[62:63], v[12:13], v[12:13]
	v_pk_mul_f32 v[64:65], v[10:11], v[10:11]
	v_mul_f32_e32 v32, v7, v7
	v_mul_f32_e32 v66, v9, v9
	v_mul_f32_e32 v83, v4, v4
	v_mul_f32_e32 v90, v5, v5
	v_mov_b32_e32 v68, v42
	v_mov_b32_e32 v69, v44
	v_mov_b32_e32 v44, v43
	v_pk_mov_b32 v[42:43], v[64:65], v[62:63] op_sel:[1,0]
	v_mov_b32_e32 v65, v63
	v_pk_fma_f32 v[62:63], v[6:7], v[6:7], v[32:33] op_sel_hi:[1,1,0]
	v_pk_fma_f32 v[66:67], v[8:9], v[8:9], v[66:67] op_sel_hi:[1,1,0]
	v_mov_b32_e32 v72, v47
	v_mov_b32_e32 v73, v51
	v_mov_b32_e32 v76, v49
	v_mov_b32_e32 v77, v53
	v_mov_b32_e32 v70, v46
	v_mov_b32_e32 v71, v50
	v_mov_b32_e32 v74, v48
	v_mov_b32_e32 v75, v52
	v_pk_mul_f32 v[78:79], v[56:57], v[56:57]
	v_pk_mul_f32 v[80:81], v[54:55], v[54:55]
	v_pk_add_f32 v[42:43], v[42:43], v[64:65]
	v_mov_b32_e32 v63, v83
	v_mov_b32_e32 v67, v90
	v_mov_b32_e32 v64, v46
	v_mov_b32_e32 v65, v48
	v_mov_b32_e32 v48, v47
	v_mov_b32_e32 v46, v50
	v_mov_b32_e32 v47, v52
	v_mov_b32_e32 v52, v51
	v_pk_mul_f32 v[50:51], v[72:73], v[72:73]
	v_pk_mul_f32 v[72:73], v[76:77], v[76:77]
	v_pk_mov_b32 v[76:77], v[80:81], v[78:79] op_sel:[1,0]
	v_mov_b32_e32 v81, v79
	v_pk_add_f32 v[62:63], v[62:63], v[66:67]
	v_pk_fma_f32 v[50:51], v[70:71], v[70:71], v[50:51]
	v_pk_fma_f32 v[66:67], v[74:75], v[74:75], v[72:73]
	v_mul_f32_e32 v32, v59, v59
	v_mul_f32_e32 v82, v61, v61
	v_pk_add_f32 v[70:71], v[76:77], v[80:81]
	v_pk_add_f32 v[50:51], v[50:51], v[66:67]
	v_mul_f32_e32 v85, v15, v15
	v_mul_f32_e32 v86, v16, v16
	v_mul_f32_e32 v87, v17, v17
	v_pk_fma_f32 v[78:79], v[58:59], v[58:59], v[32:33] op_sel_hi:[1,1,0]
	v_pk_fma_f32 v[82:83], v[60:61], v[60:61], v[82:83] op_sel_hi:[1,1,0]
	v_pk_add_f32 v[66:67], v[70:71], v[70:71] op_sel:[0,1] op_sel_hi:[1,0]
	v_pk_add_f32 v[50:51], v[50:51], v[50:51] op_sel:[0,1] op_sel_hi:[1,0]
	v_mov_b32_e32 v79, v86
	v_mov_b32_e32 v83, v87
	v_mov_b32_e32 v67, v85
	v_mov_b32_e32 v51, v84
	v_pk_add_f32 v[70:71], v[78:79], v[82:83]
	v_pk_add_f32 v[50:51], v[50:51], v[66:67]
	v_mul_f32_e32 v88, v2, v2
	v_pk_add_f32 v[50:51], v[50:51], v[70:71]
	v_mul_f32_e32 v89, v3, v3
	v_pk_add_f32 v[42:43], v[42:43], v[42:43] op_sel:[0,1] op_sel_hi:[1,0]
	v_pk_add_f32 v[50:51], v[50:51], v[50:51] op_sel:[0,1] op_sel_hi:[1,0]
	v_mov_b32_e32 v43, v89
	v_mov_b32_e32 v51, v88
	v_pk_add_f32 v[42:43], v[50:51], v[42:43]
	s_nop 0
	v_pk_add_f32 v[42:43], v[42:43], v[62:63]
	s_nop 0
	v_add_f32_e32 v32, v42, v43
	ds_bpermute_b32 v42, v33, v32
	s_waitcnt lgkmcnt(0)
	v_add_f32_e32 v32, v32, v42
	ds_bpermute_b32 v42, v34, v32
	s_waitcnt lgkmcnt(0)
	v_add_f32_e32 v32, v32, v42
	ds_bpermute_b32 v42, v35, v32
	s_waitcnt lgkmcnt(0)
	v_add_f32_e32 v32, v32, v42
	ds_bpermute_b32 v42, v36, v32
	s_waitcnt lgkmcnt(0)
	v_add_f32_e32 v32, v32, v42
	ds_bpermute_b32 v42, v37, v32
	s_waitcnt lgkmcnt(0)
	v_add_f32_e32 v32, v32, v42
	ds_bpermute_b32 v42, v38, v32
	s_waitcnt lgkmcnt(0)
	v_add_f32_e32 v32, v32, v42
	v_fmamk_f32 v32, v32, 0x3a000000, v39
	v_mul_f32_e32 v42, 0x4f800000, v32
	v_cmp_gt_f32_e32 vcc, s12, v32
	s_nop 1
	v_cndmask_b32_e32 v32, v32, v42, vcc
	v_sqrt_f32_e32 v42, v32
	s_nop 0
	v_add_u32_e32 v43, -1, v42
	v_add_u32_e32 v50, 1, v42
	v_fma_f32 v51, -v43, v42, v32
	v_fma_f32 v62, -v50, v42, v32
	v_cmp_ge_f32_e64 s[0:1], 0, v51
	s_nop 1
	v_cndmask_b32_e64 v42, v42, v43, s[0:1]
	v_cmp_lt_f32_e64 s[0:1], 0, v62
	s_nop 1
	v_cndmask_b32_e64 v42, v42, v50, s[0:1]
	v_mul_f32_e32 v43, 0x37800000, v42
	v_cndmask_b32_e32 v42, v42, v43, vcc
	v_cmp_class_f32_e32 vcc, v32, v40
	s_nop 1
	v_cndmask_b32_e32 v32, v42, v32, vcc
	v_div_scale_f32 v42, s[0:1], v32, v32, 1.0
	v_rcp_f32_e32 v50, v42
	v_div_scale_f32 v43, vcc, 1.0, v32, 1.0
	v_fma_f32 v51, -v42, v50, 1.0
	v_fmac_f32_e32 v50, v51, v50
	v_mul_f32_e32 v51, v43, v50
	v_fma_f32 v62, -v42, v51, v43
	v_fmac_f32_e32 v51, v62, v50
	v_fma_f32 v42, -v42, v51, v43
	v_div_fmas_f32 v42, v42, v50, v51
	v_div_fixup_f32 v32, v42, v32, 1.0
	v_pk_mul_f32 v[48:49], v[32:33], v[48:49] op_sel_hi:[0,1]
	v_pk_mul_f32 v[42:43], v[32:33], v[64:65] op_sel_hi:[0,1]
	v_pk_mul_f32 v[44:45], v[48:49], v[44:45]
	v_pk_mul_f32 v[42:43], v[42:43], v[68:69]
	v_and_b32_sdwa v50, v45, v41 dst_sel:DWORD dst_unused:UNUSED_PAD src0_sel:WORD_1 src1_sel:DWORD
	v_and_b32_sdwa v51, v44, v41 dst_sel:DWORD dst_unused:UNUSED_PAD src0_sel:WORD_1 src1_sel:DWORD
	v_and_b32_sdwa v48, v43, v41 dst_sel:DWORD dst_unused:UNUSED_PAD src0_sel:WORD_1 src1_sel:DWORD
	v_and_b32_sdwa v49, v42, v41 dst_sel:DWORD dst_unused:UNUSED_PAD src0_sel:WORD_1 src1_sel:DWORD
	v_add3_u32 v45, v45, v50, s13
	v_add3_u32 v44, v44, v51, s13
	v_add3_u32 v42, v42, v49, s13
	v_add3_u32 v43, v43, v48, s13
	v_and_b32_e32 v45, 0xffff0000, v45
	v_and_b32_e32 v44, 0xffff0000, v44
	v_or_b32_sdwa v43, v45, v43 dst_sel:DWORD dst_unused:UNUSED_PAD src0_sel:DWORD src1_sel:WORD_1
	v_or_b32_sdwa v42, v44, v42 dst_sel:DWORD dst_unused:UNUSED_PAD src0_sel:DWORD src1_sel:WORD_1
	flat_store_dwordx2 v[28:29], v[42:43]
	v_pk_mul_f32 v[48:49], v[32:33], v[52:53] op_sel_hi:[0,1]
	v_pk_mul_f32 v[46:47], v[32:33], v[46:47] op_sel_hi:[0,1]
	v_mov_b64_e32 v[42:43], v[144:145]
	v_mov_b64_e32 v[44:45], v[146:147]
	v_mov_b32_e32 v51, v44
	v_mov_b32_e32 v44, v43
	v_mov_b32_e32 v50, v42
	v_pk_mul_f32 v[44:45], v[48:49], v[44:45]
	v_pk_mul_f32 v[42:43], v[46:47], v[50:51]
	v_and_b32_sdwa v48, v45, v41 dst_sel:DWORD dst_unused:UNUSED_PAD src0_sel:WORD_1 src1_sel:DWORD
	v_and_b32_sdwa v49, v44, v41 dst_sel:DWORD dst_unused:UNUSED_PAD src0_sel:WORD_1 src1_sel:DWORD
	v_and_b32_sdwa v46, v43, v41 dst_sel:DWORD dst_unused:UNUSED_PAD src0_sel:WORD_1 src1_sel:DWORD
	v_and_b32_sdwa v47, v42, v41 dst_sel:DWORD dst_unused:UNUSED_PAD src0_sel:WORD_1 src1_sel:DWORD
	v_add3_u32 v45, v45, v48, s13
	v_add3_u32 v44, v44, v49, s13
	v_add3_u32 v42, v42, v47, s13
	v_add3_u32 v43, v43, v46, s13
	v_and_b32_e32 v45, 0xffff0000, v45
	v_and_b32_e32 v44, 0xffff0000, v44
	v_or_b32_sdwa v43, v45, v43 dst_sel:DWORD dst_unused:UNUSED_PAD src0_sel:DWORD src1_sel:WORD_1
	v_or_b32_sdwa v42, v44, v42 dst_sel:DWORD dst_unused:UNUSED_PAD src0_sel:DWORD src1_sel:WORD_1
	flat_store_dwordx2 v[28:29], v[42:43] offset:512
	v_mov_b32_e32 v47, v56
	v_mov_b32_e32 v56, v55
	v_mov_b32_e32 v46, v54
	v_pk_mul_f32 v[48:49], v[32:33], v[56:57] op_sel_hi:[0,1]
	v_pk_mul_f32 v[46:47], v[32:33], v[46:47] op_sel_hi:[0,1]
	v_mov_b64_e32 v[42:43], v[148:149]
	v_mov_b64_e32 v[44:45], v[150:151]
	v_mov_b32_e32 v51, v44
	v_mov_b32_e32 v44, v43
	v_mov_b32_e32 v50, v42
	v_pk_mul_f32 v[44:45], v[48:49], v[44:45]
	v_pk_mul_f32 v[42:43], v[46:47], v[50:51]
	v_and_b32_sdwa v48, v45, v41 dst_sel:DWORD dst_unused:UNUSED_PAD src0_sel:WORD_1 src1_sel:DWORD
	v_and_b32_sdwa v49, v44, v41 dst_sel:DWORD dst_unused:UNUSED_PAD src0_sel:WORD_1 src1_sel:DWORD
	v_and_b32_sdwa v46, v43, v41 dst_sel:DWORD dst_unused:UNUSED_PAD src0_sel:WORD_1 src1_sel:DWORD
	v_and_b32_sdwa v47, v42, v41 dst_sel:DWORD dst_unused:UNUSED_PAD src0_sel:WORD_1 src1_sel:DWORD
	v_add3_u32 v45, v45, v48, s13
	v_add3_u32 v44, v44, v49, s13
	v_add3_u32 v42, v42, v47, s13
	v_add3_u32 v43, v43, v46, s13
	v_and_b32_e32 v45, 0xffff0000, v45
	v_and_b32_e32 v44, 0xffff0000, v44
	v_or_b32_sdwa v43, v45, v43 dst_sel:DWORD dst_unused:UNUSED_PAD src0_sel:DWORD src1_sel:WORD_1
	v_or_b32_sdwa v42, v44, v42 dst_sel:DWORD dst_unused:UNUSED_PAD src0_sel:DWORD src1_sel:WORD_1
	flat_store_dwordx2 v[28:29], v[42:43] offset:1024
	v_mov_b32_e32 v47, v60
	v_mov_b32_e32 v60, v59
	v_mov_b32_e32 v46, v58
	v_pk_mul_f32 v[48:49], v[32:33], v[60:61] op_sel_hi:[0,1]
	v_pk_mul_f32 v[46:47], v[32:33], v[46:47] op_sel_hi:[0,1]
	v_mov_b64_e32 v[42:43], v[152:153]
	v_mov_b64_e32 v[44:45], v[154:155]
	v_mov_b32_e32 v51, v44
	v_mov_b32_e32 v44, v43
	v_mov_b32_e32 v50, v42
	v_pk_mul_f32 v[44:45], v[48:49], v[44:45]
	v_pk_mul_f32 v[42:43], v[46:47], v[50:51]
	v_and_b32_sdwa v48, v45, v41 dst_sel:DWORD dst_unused:UNUSED_PAD src0_sel:WORD_1 src1_sel:DWORD
	v_and_b32_sdwa v49, v44, v41 dst_sel:DWORD dst_unused:UNUSED_PAD src0_sel:WORD_1 src1_sel:DWORD
	v_and_b32_sdwa v46, v43, v41 dst_sel:DWORD dst_unused:UNUSED_PAD src0_sel:WORD_1 src1_sel:DWORD
	v_and_b32_sdwa v47, v42, v41 dst_sel:DWORD dst_unused:UNUSED_PAD src0_sel:WORD_1 src1_sel:DWORD
	v_add3_u32 v45, v45, v48, s13
	v_add3_u32 v44, v44, v49, s13
	v_add3_u32 v42, v42, v47, s13
	v_add3_u32 v43, v43, v46, s13
	v_and_b32_e32 v45, 0xffff0000, v45
	v_and_b32_e32 v44, 0xffff0000, v44
	v_or_b32_sdwa v43, v45, v43 dst_sel:DWORD dst_unused:UNUSED_PAD src0_sel:DWORD src1_sel:WORD_1
	v_or_b32_sdwa v42, v44, v42 dst_sel:DWORD dst_unused:UNUSED_PAD src0_sel:DWORD src1_sel:WORD_1
	flat_store_dwordx2 v[28:29], v[42:43] offset:1536
	v_mov_b32_e32 v46, v14
	v_mov_b32_e32 v47, v16
	v_mov_b32_e32 v16, v15
	v_pk_mul_f32 v[14:15], v[32:33], v[46:47] op_sel_hi:[0,1]
	v_pk_mul_f32 v[16:17], v[32:33], v[16:17] op_sel_hi:[0,1]
	v_mov_b64_e32 v[42:43], v[156:157]
	v_mov_b64_e32 v[44:45], v[158:159]
	v_mov_b32_e32 v47, v44
	v_mov_b32_e32 v44, v43
	v_mov_b32_e32 v46, v42
	v_pk_mul_f32 v[16:17], v[16:17], v[44:45]
	v_pk_mul_f32 v[14:15], v[14:15], v[46:47]
	v_and_b32_sdwa v44, v17, v41 dst_sel:DWORD dst_unused:UNUSED_PAD src0_sel:WORD_1 src1_sel:DWORD
	v_and_b32_sdwa v45, v16, v41 dst_sel:DWORD dst_unused:UNUSED_PAD src0_sel:WORD_1 src1_sel:DWORD
	v_and_b32_sdwa v42, v15, v41 dst_sel:DWORD dst_unused:UNUSED_PAD src0_sel:WORD_1 src1_sel:DWORD
	v_and_b32_sdwa v43, v14, v41 dst_sel:DWORD dst_unused:UNUSED_PAD src0_sel:WORD_1 src1_sel:DWORD
	v_add3_u32 v17, v17, v44, s13
	v_add3_u32 v16, v16, v45, s13
	v_add3_u32 v14, v14, v43, s13
	v_add3_u32 v15, v15, v42, s13
	v_and_b32_e32 v17, 0xffff0000, v17
	v_and_b32_e32 v16, 0xffff0000, v16
	v_or_b32_sdwa v15, v17, v15 dst_sel:DWORD dst_unused:UNUSED_PAD src0_sel:DWORD src1_sel:WORD_1
	v_or_b32_sdwa v14, v16, v14 dst_sel:DWORD dst_unused:UNUSED_PAD src0_sel:DWORD src1_sel:WORD_1
	flat_store_dwordx2 v[28:29], v[14:15] offset:2048
	v_mov_b32_e32 v42, v10
	v_mov_b32_e32 v43, v12
	v_mov_b32_e32 v12, v11
	v_pk_mul_f32 v[10:11], v[32:33], v[42:43] op_sel_hi:[0,1]
	v_pk_mul_f32 v[12:13], v[32:33], v[12:13] op_sel_hi:[0,1]
	v_mov_b64_e32 v[14:15], v[160:161]
	v_mov_b64_e32 v[16:17], v[162:163]
	v_mov_b32_e32 v43, v16
	v_mov_b32_e32 v16, v15
	v_mov_b32_e32 v42, v14
	v_pk_mul_f32 v[12:13], v[12:13], v[16:17]
	v_pk_mul_f32 v[10:11], v[10:11], v[42:43]
	v_and_b32_sdwa v16, v13, v41 dst_sel:DWORD dst_unused:UNUSED_PAD src0_sel:WORD_1 src1_sel:DWORD
	v_and_b32_sdwa v17, v12, v41 dst_sel:DWORD dst_unused:UNUSED_PAD src0_sel:WORD_1 src1_sel:DWORD
	v_and_b32_sdwa v14, v11, v41 dst_sel:DWORD dst_unused:UNUSED_PAD src0_sel:WORD_1 src1_sel:DWORD
	v_and_b32_sdwa v15, v10, v41 dst_sel:DWORD dst_unused:UNUSED_PAD src0_sel:WORD_1 src1_sel:DWORD
	v_add3_u32 v13, v13, v16, s13
	v_add3_u32 v12, v12, v17, s13
	v_add3_u32 v10, v10, v15, s13
	v_add3_u32 v11, v11, v14, s13
	v_and_b32_e32 v13, 0xffff0000, v13
	v_and_b32_e32 v12, 0xffff0000, v12
	v_or_b32_sdwa v11, v13, v11 dst_sel:DWORD dst_unused:UNUSED_PAD src0_sel:DWORD src1_sel:WORD_1
	v_or_b32_sdwa v10, v12, v10 dst_sel:DWORD dst_unused:UNUSED_PAD src0_sel:DWORD src1_sel:WORD_1
	flat_store_dwordx2 v[28:29], v[10:11] offset:2560
	v_mov_b32_e32 v14, v6
	v_mov_b32_e32 v15, v8
	v_mov_b32_e32 v8, v7
	v_pk_mul_f32 v[6:7], v[32:33], v[14:15] op_sel_hi:[0,1]
	v_pk_mul_f32 v[8:9], v[32:33], v[8:9] op_sel_hi:[0,1]
	v_mov_b64_e32 v[10:11], v[164:165]
	v_mov_b64_e32 v[12:13], v[166:167]
	v_mov_b32_e32 v15, v12
	v_mov_b32_e32 v12, v11
	v_mov_b32_e32 v14, v10
	v_pk_mul_f32 v[8:9], v[8:9], v[12:13]
	v_pk_mul_f32 v[6:7], v[6:7], v[14:15]
	v_and_b32_sdwa v12, v9, v41 dst_sel:DWORD dst_unused:UNUSED_PAD src0_sel:WORD_1 src1_sel:DWORD
	v_and_b32_sdwa v13, v8, v41 dst_sel:DWORD dst_unused:UNUSED_PAD src0_sel:WORD_1 src1_sel:DWORD
	v_and_b32_sdwa v10, v7, v41 dst_sel:DWORD dst_unused:UNUSED_PAD src0_sel:WORD_1 src1_sel:DWORD
	v_and_b32_sdwa v11, v6, v41 dst_sel:DWORD dst_unused:UNUSED_PAD src0_sel:WORD_1 src1_sel:DWORD
	v_add3_u32 v9, v9, v12, s13
	v_add3_u32 v8, v8, v13, s13
	v_add3_u32 v6, v6, v11, s13
	v_add3_u32 v7, v7, v10, s13
	v_and_b32_e32 v9, 0xffff0000, v9
	v_and_b32_e32 v8, 0xffff0000, v8
	v_or_b32_sdwa v7, v9, v7 dst_sel:DWORD dst_unused:UNUSED_PAD src0_sel:DWORD src1_sel:WORD_1
	v_or_b32_sdwa v6, v8, v6 dst_sel:DWORD dst_unused:UNUSED_PAD src0_sel:DWORD src1_sel:WORD_1
	flat_store_dwordx2 v[28:29], v[6:7] offset:3072
	v_mov_b32_e32 v10, v2
	v_mov_b32_e32 v11, v4
	v_mov_b32_e32 v4, v3
	v_pk_mul_f32 v[2:3], v[32:33], v[10:11] op_sel_hi:[0,1]
	v_pk_mul_f32 v[4:5], v[32:33], v[4:5] op_sel_hi:[0,1]
	v_mov_b64_e32 v[6:7], v[168:169]
	v_mov_b64_e32 v[8:9], v[170:171]
	v_mov_b32_e32 v11, v8
	v_mov_b32_e32 v8, v7
	v_mov_b32_e32 v10, v6
	v_pk_mul_f32 v[4:5], v[4:5], v[8:9]
	v_pk_mul_f32 v[2:3], v[2:3], v[10:11]
	v_and_b32_sdwa v8, v5, v41 dst_sel:DWORD dst_unused:UNUSED_PAD src0_sel:WORD_1 src1_sel:DWORD
	v_and_b32_sdwa v9, v4, v41 dst_sel:DWORD dst_unused:UNUSED_PAD src0_sel:WORD_1 src1_sel:DWORD
	v_and_b32_sdwa v6, v3, v41 dst_sel:DWORD dst_unused:UNUSED_PAD src0_sel:WORD_1 src1_sel:DWORD
	v_and_b32_sdwa v7, v2, v41 dst_sel:DWORD dst_unused:UNUSED_PAD src0_sel:WORD_1 src1_sel:DWORD
	v_add3_u32 v5, v5, v8, s13
	v_add3_u32 v4, v4, v9, s13
	v_add3_u32 v2, v2, v7, s13
	v_add3_u32 v3, v3, v6, s13
	v_and_b32_e32 v5, 0xffff0000, v5
	v_and_b32_e32 v4, 0xffff0000, v4
	v_or_b32_sdwa v3, v5, v3 dst_sel:DWORD dst_unused:UNUSED_PAD src0_sel:DWORD src1_sel:WORD_1
	v_or_b32_sdwa v2, v4, v2 dst_sel:DWORD dst_unused:UNUSED_PAD src0_sel:DWORD src1_sel:WORD_1
	flat_store_dwordx2 v[28:29], v[2:3] offset:3584
	v_lshl_add_u64 v[28:29], v[28:29], 0, s[6:7]
	s_cbranch_scc0 .LBB0_85
